# up epilogue: conv-tap FMAs and gate multiplies as packed f32 (v_pk_fma_f32 / v_pk_mul_f32), on top of the dwordx4 row-pair stores
# speedup vs baseline: 1.0076x; 1.0051x over previous
.LBB0_104:
	s_add_u32 s2, s34, 0xfffc2080
	s_addc_u32 s3, s35, -1
	s_add_i32 s12, 0, 0x10000
	v_add_u32_e32 v110, s12, v179
	ds_read_b128 v[98:101], v110
	ds_read_b128 v[102:105], v110 offset:1024
	ds_read_b128 v[106:109], v110 offset:2048
	ds_read_b128 v[110:113], v110 offset:3072
	s_cmp_eq_u32 s53, 12
	s_cselect_b32 s49, s97, s3
	s_cselect_b32 s48, s96, s2
	s_cselect_b32 s3, s1, s52
	s_cselect_b32 s2, s23, s51
	v_lshl_add_u64 v[174:175], s[34:35], 0, v[170:171]
	s_add_i32 m0, s85, 0xc000
	ds_read_b128 v[114:117], v184
	ds_read_b128 v[118:121], v184 offset:1024
	ds_read_b128 v[122:125], v184 offset:2048
	ds_read_b128 v[126:129], v184 offset:3072
	ds_read_b128 v[186:189], v184 offset:4096
	ds_read_b128 v[190:193], v184 offset:5120
	ds_read_b128 v[194:197], v184 offset:6144
	ds_read_b128 v[198:201], v184 offset:7168
	global_load_lds_dwordx4 v[174:175], off
	v_lshl_add_u64 v[174:175], s[34:35], 0, v[172:173]
	s_add_i32 m0, s85, 0xe000
	s_nop 0
	global_load_lds_dwordx4 v[174:175], off
	s_waitcnt lgkmcnt(8)
	s_barrier
	s_waitcnt lgkmcnt(0)
	s_waitcnt lgkmcnt(0)
	v_mfma_f32_16x16x32_bf16 v[158:161], v[98:101], v[114:117], v[158:161]
	v_mfma_f32_16x16x32_bf16 v[154:157], v[106:109], v[114:117], v[154:157]
	v_mfma_f32_16x16x32_bf16 v[150:153], v[98:101], v[122:125], v[150:153]
	v_mfma_f32_16x16x32_bf16 v[146:149], v[106:109], v[122:125], v[146:149]
	v_mfma_f32_16x16x32_bf16 v[142:145], v[98:101], v[186:189], v[142:145]
	v_mfma_f32_16x16x32_bf16 v[138:141], v[106:109], v[186:189], v[138:141]
	v_mfma_f32_16x16x32_bf16 v[134:137], v[98:101], v[194:197], v[134:137]
	v_mfma_f32_16x16x32_bf16 v[130:133], v[106:109], v[194:197], v[130:133]
	v_mfma_f32_16x16x32_bf16 v[158:161], v[102:105], v[118:121], v[158:161]
	v_mfma_f32_16x16x32_bf16 v[154:157], v[110:113], v[118:121], v[154:157]
	v_mfma_f32_16x16x32_bf16 v[150:153], v[102:105], v[126:129], v[150:153]
	v_mfma_f32_16x16x32_bf16 v[146:149], v[110:113], v[126:129], v[146:149]
	v_mfma_f32_16x16x32_bf16 v[142:145], v[102:105], v[190:193], v[142:145]
	v_mfma_f32_16x16x32_bf16 v[138:141], v[110:113], v[190:193], v[138:141]
	v_mfma_f32_16x16x32_bf16 v[134:137], v[102:105], v[198:201], v[134:137]
	v_mfma_f32_16x16x32_bf16 v[130:133], v[110:113], v[198:201], v[130:133]
	s_barrier
	s_add_i32 s54, 0, 0x14000
	v_add_u32_e32 v174, s54, v179
	s_add_i32 s12, s12, s78
	ds_read_b128 v[226:229], v174
	ds_read_b128 v[230:233], v174 offset:1024
	ds_read_b128 v[234:237], v174 offset:2048
	ds_read_b128 v[242:245], v174 offset:3072
	v_lshl_add_u64 v[174:175], s[2:3], 0, v[0:1]
	s_mov_b32 m0, s12
	v_lshl_add_u64 v[246:247], s[2:3], 0, v[166:167]
	global_load_lds_dwordx4 v[174:175], off
	s_add_i32 m0, s12, 0x2000
	s_nop 0
	global_load_lds_dwordx4 v[246:247], off
	s_barrier
	s_waitcnt lgkmcnt(0)
	s_waitcnt lgkmcnt(0)
	v_mfma_f32_16x16x32_bf16 v[62:65], v[226:229], v[114:117], v[62:65]
	v_mfma_f32_16x16x32_bf16 v[58:61], v[234:237], v[114:117], v[58:61]
	v_mfma_f32_16x16x32_bf16 v[54:57], v[226:229], v[122:125], v[54:57]
	v_mfma_f32_16x16x32_bf16 v[50:53], v[234:237], v[122:125], v[50:53]
	v_mfma_f32_16x16x32_bf16 v[46:49], v[226:229], v[186:189], v[46:49]
	v_mfma_f32_16x16x32_bf16 v[42:45], v[234:237], v[186:189], v[42:45]
	v_mfma_f32_16x16x32_bf16 v[38:41], v[226:229], v[194:197], v[38:41]
	v_mfma_f32_16x16x32_bf16 v[34:37], v[234:237], v[194:197], v[34:37]
	v_mfma_f32_16x16x32_bf16 v[62:65], v[230:233], v[118:121], v[62:65]
	v_mfma_f32_16x16x32_bf16 v[58:61], v[242:245], v[118:121], v[58:61]
	v_mfma_f32_16x16x32_bf16 v[54:57], v[230:233], v[126:129], v[54:57]
	v_mfma_f32_16x16x32_bf16 v[50:53], v[242:245], v[126:129], v[50:53]
	v_mfma_f32_16x16x32_bf16 v[46:49], v[230:233], v[190:193], v[46:49]
	v_mfma_f32_16x16x32_bf16 v[42:45], v[242:245], v[190:193], v[42:45]
	v_mfma_f32_16x16x32_bf16 v[38:41], v[230:233], v[198:201], v[38:41]
	v_mfma_f32_16x16x32_bf16 v[34:37], v[242:245], v[198:201], v[34:37]
	s_mov_b32 m0, s85
	v_lshl_add_u64 v[248:249], s[48:49], 0, v[162:163]
	s_barrier
	ds_read_b128 v[114:117], v184 offset:16384
	ds_read_b128 v[118:121], v184 offset:17408
	ds_read_b128 v[122:125], v184 offset:18432
	ds_read_b128 v[126:129], v184 offset:19456
	ds_read_b128 v[186:189], v184 offset:20480
	ds_read_b128 v[190:193], v184 offset:21504
	ds_read_b128 v[194:197], v184 offset:22528
	ds_read_b128 v[198:201], v184 offset:23552
	global_load_lds_dwordx4 v[248:249], off
	v_lshl_add_u64 v[250:251], s[48:49], 0, v[164:165]
	s_mov_b32 m0, s82
	s_nop 0
	global_load_lds_dwordx4 v[250:251], off
	s_barrier
	s_waitcnt lgkmcnt(0)
	s_waitcnt lgkmcnt(0)
	v_mfma_f32_16x16x32_bf16 v[94:97], v[98:101], v[114:117], v[94:97]
	v_mfma_f32_16x16x32_bf16 v[90:93], v[106:109], v[114:117], v[90:93]
	v_mfma_f32_16x16x32_bf16 v[86:89], v[98:101], v[122:125], v[86:89]
	v_mfma_f32_16x16x32_bf16 v[82:85], v[106:109], v[122:125], v[82:85]
	v_mfma_f32_16x16x32_bf16 v[78:81], v[98:101], v[186:189], v[78:81]
	v_mfma_f32_16x16x32_bf16 v[74:77], v[106:109], v[186:189], v[74:77]
	v_mfma_f32_16x16x32_bf16 v[70:73], v[98:101], v[194:197], v[70:73]
	v_mfma_f32_16x16x32_bf16 v[66:69], v[106:109], v[194:197], v[66:69]
	v_mfma_f32_16x16x32_bf16 v[94:97], v[102:105], v[118:121], v[94:97]
	v_mfma_f32_16x16x32_bf16 v[90:93], v[110:113], v[118:121], v[90:93]
	v_mfma_f32_16x16x32_bf16 v[86:89], v[102:105], v[126:129], v[86:89]
	v_mfma_f32_16x16x32_bf16 v[82:85], v[110:113], v[126:129], v[82:85]
	v_mfma_f32_16x16x32_bf16 v[78:81], v[102:105], v[190:193], v[78:81]
	v_mfma_f32_16x16x32_bf16 v[74:77], v[110:113], v[190:193], v[74:77]
	v_mfma_f32_16x16x32_bf16 v[70:73], v[102:105], v[198:201], v[70:73]
	v_mfma_f32_16x16x32_bf16 v[66:69], v[110:113], v[198:201], v[66:69]
	s_barrier
	s_add_u32 s12, s2, 0x40000
	s_addc_u32 s13, s3, 0
	s_add_i32 s54, s54, s78
	v_lshl_add_u64 v[98:99], s[12:13], 0, v[0:1]
	s_mov_b32 m0, s54
	s_nop 0
	global_load_lds_dwordx4 v[98:99], off
	v_lshl_add_u64 v[98:99], s[12:13], 0, v[166:167]
	s_add_i32 m0, s54, 0x2000
	s_nop 0
	global_load_lds_dwordx4 v[98:99], off
	s_waitcnt vmcnt(6)
	s_barrier
	v_mfma_f32_16x16x32_bf16 v[30:33], v[226:229], v[114:117], v[30:33]
	v_mfma_f32_16x16x32_bf16 v[26:29], v[234:237], v[114:117], v[26:29]
	v_mfma_f32_16x16x32_bf16 v[22:25], v[226:229], v[122:125], v[22:25]
	v_mfma_f32_16x16x32_bf16 v[18:21], v[234:237], v[122:125], v[18:21]
	v_mfma_f32_16x16x32_bf16 v[14:17], v[226:229], v[186:189], v[14:17]
	v_mfma_f32_16x16x32_bf16 v[10:13], v[234:237], v[186:189], v[10:13]
	v_mfma_f32_16x16x32_bf16 v[6:9], v[226:229], v[194:197], v[6:9]
	v_mfma_f32_16x16x32_bf16 v[2:5], v[234:237], v[194:197], v[2:5]
	v_mfma_f32_16x16x32_bf16 v[30:33], v[230:233], v[118:121], v[30:33]
	v_mfma_f32_16x16x32_bf16 v[26:29], v[242:245], v[118:121], v[26:29]
	v_mfma_f32_16x16x32_bf16 v[22:25], v[230:233], v[126:129], v[22:25]
	v_mfma_f32_16x16x32_bf16 v[18:21], v[242:245], v[126:129], v[18:21]
	v_mfma_f32_16x16x32_bf16 v[14:17], v[230:233], v[190:193], v[14:17]
	v_mfma_f32_16x16x32_bf16 v[10:13], v[242:245], v[190:193], v[10:13]
	v_mfma_f32_16x16x32_bf16 v[6:9], v[230:233], v[198:201], v[6:9]
	v_mfma_f32_16x16x32_bf16 v[2:5], v[242:245], v[198:201], v[2:5]
	s_add_i32 s54, 0, 0x18000
	v_add_u32_e32 v110, s54, v179
	s_barrier
	ds_read_b128 v[98:101], v110
	ds_read_b128 v[102:105], v110 offset:1024
	ds_read_b128 v[106:109], v110 offset:2048
	ds_read_b128 v[110:113], v110 offset:3072
	s_add_u32 s12, s48, 0x3e000
	s_addc_u32 s13, s49, 0
	s_mov_b32 m0, s89
	v_lshl_add_u64 v[226:227], s[12:13], 0, v[162:163]
	ds_read_b128 v[114:117], v184 offset:32768
	ds_read_b128 v[118:121], v184 offset:33792
	ds_read_b128 v[122:125], v184 offset:34816
	ds_read_b128 v[126:129], v184 offset:35840
	ds_read_b128 v[186:189], v184 offset:36864
	ds_read_b128 v[190:193], v184 offset:37888
	ds_read_b128 v[194:197], v184 offset:38912
	ds_read_b128 v[198:201], v184 offset:39936
	global_load_lds_dwordx4 v[226:227], off
	v_lshl_add_u64 v[226:227], s[12:13], 0, v[164:165]
	s_mov_b32 m0, s91
	s_nop 0
	global_load_lds_dwordx4 v[226:227], off
	s_waitcnt lgkmcnt(8)
	s_barrier
	s_waitcnt lgkmcnt(0)
	s_waitcnt lgkmcnt(0)
	v_mfma_f32_16x16x32_bf16 v[158:161], v[98:101], v[114:117], v[158:161]
	v_mfma_f32_16x16x32_bf16 v[154:157], v[106:109], v[114:117], v[154:157]
	v_mfma_f32_16x16x32_bf16 v[150:153], v[98:101], v[122:125], v[150:153]
	v_mfma_f32_16x16x32_bf16 v[146:149], v[106:109], v[122:125], v[146:149]
	v_mfma_f32_16x16x32_bf16 v[142:145], v[98:101], v[186:189], v[142:145]
	v_mfma_f32_16x16x32_bf16 v[138:141], v[106:109], v[186:189], v[138:141]
	v_mfma_f32_16x16x32_bf16 v[134:137], v[98:101], v[194:197], v[134:137]
	v_mfma_f32_16x16x32_bf16 v[130:133], v[106:109], v[194:197], v[130:133]
	v_mfma_f32_16x16x32_bf16 v[158:161], v[102:105], v[118:121], v[158:161]
	v_mfma_f32_16x16x32_bf16 v[154:157], v[110:113], v[118:121], v[154:157]
	v_mfma_f32_16x16x32_bf16 v[150:153], v[102:105], v[126:129], v[150:153]
	v_mfma_f32_16x16x32_bf16 v[146:149], v[110:113], v[126:129], v[146:149]
	v_mfma_f32_16x16x32_bf16 v[142:145], v[102:105], v[190:193], v[142:145]
	v_mfma_f32_16x16x32_bf16 v[138:141], v[110:113], v[190:193], v[138:141]
	v_mfma_f32_16x16x32_bf16 v[134:137], v[102:105], v[198:201], v[134:137]
	v_mfma_f32_16x16x32_bf16 v[130:133], v[110:113], v[198:201], v[130:133]
	s_barrier
	s_add_i32 s12, 0, 0x1c000
	s_add_i32 s13, s54, s78
	v_add_u32_e32 v242, s12, v179
	v_lshl_add_u64 v[174:175], v[174:175], 0, s[20:21]
	s_mov_b32 m0, s13
	ds_read_b128 v[226:229], v242
	ds_read_b128 v[230:233], v242 offset:1024
	ds_read_b128 v[234:237], v242 offset:2048
	ds_read_b128 v[242:245], v242 offset:3072
	global_load_lds_dwordx4 v[174:175], off
	v_lshl_add_u64 v[174:175], v[246:247], 0, s[20:21]
	s_add_i32 m0, s13, 0x2000
	s_nop 0
	global_load_lds_dwordx4 v[174:175], off
	s_barrier
	s_waitcnt lgkmcnt(0)
	s_waitcnt lgkmcnt(0)
	v_mfma_f32_16x16x32_bf16 v[62:65], v[226:229], v[114:117], v[62:65]
	v_mfma_f32_16x16x32_bf16 v[58:61], v[234:237], v[114:117], v[58:61]
	v_mfma_f32_16x16x32_bf16 v[54:57], v[226:229], v[122:125], v[54:57]
	v_mfma_f32_16x16x32_bf16 v[50:53], v[234:237], v[122:125], v[50:53]
	v_mfma_f32_16x16x32_bf16 v[46:49], v[226:229], v[186:189], v[46:49]
	v_mfma_f32_16x16x32_bf16 v[42:45], v[234:237], v[186:189], v[42:45]
	v_mfma_f32_16x16x32_bf16 v[38:41], v[226:229], v[194:197], v[38:41]
	v_mfma_f32_16x16x32_bf16 v[34:37], v[234:237], v[194:197], v[34:37]
	v_mfma_f32_16x16x32_bf16 v[62:65], v[230:233], v[118:121], v[62:65]
	v_mfma_f32_16x16x32_bf16 v[58:61], v[242:245], v[118:121], v[58:61]
	v_mfma_f32_16x16x32_bf16 v[54:57], v[230:233], v[126:129], v[54:57]
	v_mfma_f32_16x16x32_bf16 v[50:53], v[242:245], v[126:129], v[50:53]
	v_mfma_f32_16x16x32_bf16 v[46:49], v[230:233], v[190:193], v[46:49]
	v_mfma_f32_16x16x32_bf16 v[42:45], v[242:245], v[190:193], v[42:45]
	v_mfma_f32_16x16x32_bf16 v[38:41], v[230:233], v[198:201], v[38:41]
	v_mfma_f32_16x16x32_bf16 v[34:37], v[242:245], v[198:201], v[34:37]
	s_mov_b32 m0, s79
	v_lshl_add_u64 v[174:175], v[248:249], 0, s[20:21]
	s_barrier
	ds_read_b128 v[114:117], v184 offset:49152
	ds_read_b128 v[118:121], v184 offset:50176
	ds_read_b128 v[122:125], v184 offset:51200
	ds_read_b128 v[126:129], v184 offset:52224
	ds_read_b128 v[186:189], v184 offset:53248
	ds_read_b128 v[190:193], v184 offset:54272
	ds_read_b128 v[194:197], v184 offset:55296
	ds_read_b128 v[198:201], v184 offset:56320
	global_load_lds_dwordx4 v[174:175], off
	v_lshl_add_u64 v[174:175], v[250:251], 0, s[20:21]
	s_mov_b32 m0, s87
	s_nop 0
	global_load_lds_dwordx4 v[174:175], off
	s_barrier
	s_waitcnt lgkmcnt(0)
	s_waitcnt lgkmcnt(0)
	v_mfma_f32_16x16x32_bf16 v[94:97], v[98:101], v[114:117], v[94:97]
	v_mfma_f32_16x16x32_bf16 v[90:93], v[106:109], v[114:117], v[90:93]
	v_mfma_f32_16x16x32_bf16 v[86:89], v[98:101], v[122:125], v[86:89]
	v_mfma_f32_16x16x32_bf16 v[82:85], v[106:109], v[122:125], v[82:85]
	v_mfma_f32_16x16x32_bf16 v[78:81], v[98:101], v[186:189], v[78:81]
	v_mfma_f32_16x16x32_bf16 v[74:77], v[106:109], v[186:189], v[74:77]
	v_mfma_f32_16x16x32_bf16 v[70:73], v[98:101], v[194:197], v[70:73]
	v_mfma_f32_16x16x32_bf16 v[66:69], v[106:109], v[194:197], v[66:69]
	v_mfma_f32_16x16x32_bf16 v[94:97], v[102:105], v[118:121], v[94:97]
	v_mfma_f32_16x16x32_bf16 v[90:93], v[110:113], v[118:121], v[90:93]
	v_mfma_f32_16x16x32_bf16 v[86:89], v[102:105], v[126:129], v[86:89]
	v_mfma_f32_16x16x32_bf16 v[82:85], v[110:113], v[126:129], v[82:85]
	v_mfma_f32_16x16x32_bf16 v[78:81], v[102:105], v[190:193], v[78:81]
	v_mfma_f32_16x16x32_bf16 v[74:77], v[110:113], v[190:193], v[74:77]
	v_mfma_f32_16x16x32_bf16 v[70:73], v[102:105], v[198:201], v[70:73]
	v_mfma_f32_16x16x32_bf16 v[66:69], v[110:113], v[198:201], v[66:69]
	s_barrier
	s_add_u32 s2, s2, 0x40080
	s_addc_u32 s3, s3, 0
	s_add_i32 s12, s12, s78
	v_lshl_add_u64 v[98:99], s[2:3], 0, v[0:1]
	s_mov_b32 m0, s12
	s_nop 0
	global_load_lds_dwordx4 v[98:99], off
	v_lshl_add_u64 v[98:99], s[2:3], 0, v[166:167]
	s_add_i32 m0, s12, 0x2000
	s_nop 0
	global_load_lds_dwordx4 v[98:99], off
	s_waitcnt vmcnt(6)
	s_barrier
	v_mfma_f32_16x16x32_bf16 v[30:33], v[226:229], v[114:117], v[30:33]
	v_mfma_f32_16x16x32_bf16 v[26:29], v[234:237], v[114:117], v[26:29]
	v_mfma_f32_16x16x32_bf16 v[22:25], v[226:229], v[122:125], v[22:25]
	v_mfma_f32_16x16x32_bf16 v[18:21], v[234:237], v[122:125], v[18:21]
	v_mfma_f32_16x16x32_bf16 v[14:17], v[226:229], v[186:189], v[14:17]
	v_mfma_f32_16x16x32_bf16 v[10:13], v[234:237], v[186:189], v[10:13]
	v_mfma_f32_16x16x32_bf16 v[6:9], v[226:229], v[194:197], v[6:9]
	v_mfma_f32_16x16x32_bf16 v[2:5], v[234:237], v[194:197], v[2:5]
	v_mfma_f32_16x16x32_bf16 v[30:33], v[230:233], v[118:121], v[30:33]
	v_mfma_f32_16x16x32_bf16 v[26:29], v[242:245], v[118:121], v[26:29]
	v_mfma_f32_16x16x32_bf16 v[22:25], v[230:233], v[126:129], v[22:25]
	v_mfma_f32_16x16x32_bf16 v[18:21], v[242:245], v[126:129], v[18:21]
	v_mfma_f32_16x16x32_bf16 v[14:17], v[230:233], v[190:193], v[14:17]
	v_mfma_f32_16x16x32_bf16 v[10:13], v[242:245], v[190:193], v[10:13]
	v_mfma_f32_16x16x32_bf16 v[6:9], v[230:233], v[198:201], v[6:9]
	v_mfma_f32_16x16x32_bf16 v[2:5], v[242:245], v[198:201], v[2:5]
	s_add_i32 s53, s53, 2
	s_add_u32 s34, s34, 0x100
	s_addc_u32 s35, s35, 0
	s_add_u32 s51, s51, 0x100
	s_addc_u32 s52, s52, 0
	s_cmp_gt_u32 s53, 13
	s_barrier
	s_cbranch_scc0 .LBB0_104
	s_add_i32 s1, s50, 0xffffffbd
	s_cmpk_gt_i32 s50, 0x42
	s_cselect_b32 s1, s1, s50
	s_mul_i32 s23, s1, 0xf8
	s_cselect_b32 s2, 0x4000, 0
	s_cselect_b32 s3, 0x100, s37
	s_add_i32 s23, s23, s84
	v_add_u32_e32 v188, s88, v178
	s_mov_b32 s50, 0xbfb8aa3b
	s_mov_b32 s51, 0xbfb8aa3b
	ds_read_b128 v[126:129], v188
	ds_read_b128 v[122:125], v188 offset:128
	ds_read_b128 v[114:117], v188 offset:256
	ds_read_b128 v[118:121], v188 offset:384
	ds_read_b128 v[110:113], v188 offset:512
	ds_read_b128 v[106:109], v188 offset:640
	ds_read_b128 v[98:101], v188 offset:768
	ds_read_b128 v[102:105], v188 offset:896
	v_readlane_b32 s12, v252, 28
	v_readlane_b32 s13, v252, 29
	v_bfe_u32 v231, v202, 5, 1
	v_and_b32_e32 v174, 48, v180
	v_lshl_or_b32 v174, v231, 3, v174
	v_lshl_or_b32 v174, s0, 7, v174
	v_bfe_u32 v230, v202, 4, 1
	v_lshl_add_u32 v186, v177, 2, s23
	v_cmp_eq_u32_e32 vcc, 1, v230
	s_or_b64 s[52:53], s[42:43], vcc
	v_cmp_eq_u32_e32 vcc, 0, v230
	s_or_b64 s[54:55], s[44:45], vcc
	v_add_u32_e32 v186, v186, v230
	v_add_u32_e32 v187, s2, v186
	v_mul_u32_u24_e32 v187, 0x1600, v187
	v_lshl_add_u32 v187, v174, 1, v187
	s_waitcnt lgkmcnt(0)
	v_pk_fma_f32 v[190:191], v[158:159], v[122:123], v[118:119]
	v_pk_fma_f32 v[192:193], v[160:161], v[124:125], v[120:121]
	v_pk_fma_f32 v[194:195], v[154:155], v[106:107], v[102:103]
	v_pk_fma_f32 v[196:197], v[156:157], v[108:109], v[104:105]
	v_add_u32_e32 v230, 0, v186
	v_fmac_f32_dpp v190, v134, v126 row_ror:1 row_mask:0xf bank_mask:0xf
	v_fmac_f32_dpp v191, v135, v127 row_ror:1 row_mask:0xf bank_mask:0xf
	v_fmac_f32_dpp v192, v136, v128 row_ror:1 row_mask:0xf bank_mask:0xf
	v_fmac_f32_dpp v193, v137, v129 row_ror:1 row_mask:0xf bank_mask:0xf
	v_fmac_f32_dpp v194, v130, v110 row_ror:1 row_mask:0xf bank_mask:0xf
	v_fmac_f32_dpp v195, v131, v111 row_ror:1 row_mask:0xf bank_mask:0xf
	v_fmac_f32_dpp v196, v132, v112 row_ror:1 row_mask:0xf bank_mask:0xf
	v_fmac_f32_dpp v197, v133, v113 row_ror:1 row_mask:0xf bank_mask:0xf
	v_pk_fma_f32 v[190:191], v[150:151], v[114:115], v[190:191]
	v_pk_fma_f32 v[192:193], v[152:153], v[116:117], v[192:193]
	v_pk_fma_f32 v[194:195], v[146:147], v[98:99], v[194:195]
	v_pk_fma_f32 v[196:197], v[148:149], v[100:101], v[196:197]
	v_pk_mul_f32 v[198:199], v[190:191], s[50:51]
	v_pk_mul_f32 v[200:201], v[192:193], s[50:51]
	v_exp_f32_e32 v198, v198
	v_exp_f32_e32 v199, v199
	v_exp_f32_e32 v200, v200
	v_exp_f32_e32 v201, v201
	v_add_f32_e32 v198, 1.0, v198
	v_add_f32_e32 v199, 1.0, v199
	v_add_f32_e32 v200, 1.0, v200
	v_add_f32_e32 v201, 1.0, v201
	v_rcp_f32_e32 v198, v198
	v_rcp_f32_e32 v199, v199
	v_rcp_f32_e32 v200, v200
	v_rcp_f32_e32 v201, v201
	v_pk_mul_f32 v[190:191], v[190:191], v[198:199]
	v_pk_mul_f32 v[192:193], v[192:193], v[200:201]
	v_pk_mul_f32 v[190:191], v[190:191], v[194:195]
	v_pk_mul_f32 v[192:193], v[192:193], v[196:197]
	v_cvt_pk_bf16_f32 v232, v190, v191
	v_cvt_pk_bf16_f32 v233, v192, v193
	v_pk_fma_f32 v[190:191], v[150:151], v[122:123], v[118:119]
	v_pk_fma_f32 v[192:193], v[152:153], v[124:125], v[120:121]
	v_pk_fma_f32 v[194:195], v[146:147], v[106:107], v[102:103]
	v_pk_fma_f32 v[196:197], v[148:149], v[108:109], v[104:105]
	v_pk_fma_f32 v[190:191], v[158:159], v[126:127], v[190:191]
	v_pk_fma_f32 v[192:193], v[160:161], v[128:129], v[192:193]
	v_pk_fma_f32 v[194:195], v[154:155], v[110:111], v[194:195]
	v_pk_fma_f32 v[196:197], v[156:157], v[112:113], v[196:197]
	v_pk_fma_f32 v[190:191], v[142:143], v[114:115], v[190:191]
	v_pk_fma_f32 v[192:193], v[144:145], v[116:117], v[192:193]
	v_pk_fma_f32 v[194:195], v[138:139], v[98:99], v[194:195]
	v_pk_fma_f32 v[196:197], v[140:141], v[100:101], v[196:197]
	v_pk_mul_f32 v[198:199], v[190:191], s[50:51]
	v_pk_mul_f32 v[200:201], v[192:193], s[50:51]
	v_exp_f32_e32 v198, v198
	v_exp_f32_e32 v199, v199
	v_exp_f32_e32 v200, v200
	v_exp_f32_e32 v201, v201
	v_add_f32_e32 v198, 1.0, v198
	v_add_f32_e32 v199, 1.0, v199
	v_add_f32_e32 v200, 1.0, v200
	v_add_f32_e32 v201, 1.0, v201
	v_rcp_f32_e32 v198, v198
	v_rcp_f32_e32 v199, v199
	v_rcp_f32_e32 v200, v200
	v_rcp_f32_e32 v201, v201
	v_pk_mul_f32 v[190:191], v[190:191], v[198:199]
	v_pk_mul_f32 v[192:193], v[192:193], v[200:201]
	v_pk_mul_f32 v[190:191], v[190:191], v[194:195]
	v_pk_mul_f32 v[192:193], v[192:193], v[196:197]
	v_cvt_pk_bf16_f32 v234, v190, v191
	v_cvt_pk_bf16_f32 v235, v192, v193
	v_cmp_gt_i32_e32 vcc, s3, v230
	s_and_b64 vcc, vcc, s[52:53]
	s_nop 0
	v_permlane16_swap_b32_e32 v232, v234
	v_permlane16_swap_b32_e32 v233, v235
	s_and_saveexec_b64 s[0:1], vcc
	global_store_dwordx4 v187, v[232:235], s[12:13]
	s_mov_b64 exec, s[0:1]
	v_pk_fma_f32 v[190:191], v[142:143], v[122:123], v[118:119]
	v_pk_fma_f32 v[192:193], v[144:145], v[124:125], v[120:121]
	v_pk_fma_f32 v[194:195], v[138:139], v[106:107], v[102:103]
	v_pk_fma_f32 v[196:197], v[140:141], v[108:109], v[104:105]
	v_add_u32_e32 v230, 2, v186
	v_add_u32_e32 v231, 0x2c00, v187
	v_pk_fma_f32 v[190:191], v[150:151], v[126:127], v[190:191]
	v_pk_fma_f32 v[192:193], v[152:153], v[128:129], v[192:193]
	v_pk_fma_f32 v[194:195], v[146:147], v[110:111], v[194:195]
	v_pk_fma_f32 v[196:197], v[148:149], v[112:113], v[196:197]
	v_pk_fma_f32 v[190:191], v[134:135], v[114:115], v[190:191]
	v_pk_fma_f32 v[192:193], v[136:137], v[116:117], v[192:193]
	v_pk_fma_f32 v[194:195], v[130:131], v[98:99], v[194:195]
	v_pk_fma_f32 v[196:197], v[132:133], v[100:101], v[196:197]
	v_pk_mul_f32 v[198:199], v[190:191], s[50:51]
	v_pk_mul_f32 v[200:201], v[192:193], s[50:51]
	v_exp_f32_e32 v198, v198
	v_exp_f32_e32 v199, v199
	v_exp_f32_e32 v200, v200
	v_exp_f32_e32 v201, v201
	v_add_f32_e32 v198, 1.0, v198
	v_add_f32_e32 v199, 1.0, v199
	v_add_f32_e32 v200, 1.0, v200
	v_add_f32_e32 v201, 1.0, v201
	v_rcp_f32_e32 v198, v198
	v_rcp_f32_e32 v199, v199
	v_rcp_f32_e32 v200, v200
	v_rcp_f32_e32 v201, v201
	v_pk_mul_f32 v[190:191], v[190:191], v[198:199]
	v_pk_mul_f32 v[192:193], v[192:193], v[200:201]
	v_pk_mul_f32 v[190:191], v[190:191], v[194:195]
	v_pk_mul_f32 v[192:193], v[192:193], v[196:197]
	v_cvt_pk_bf16_f32 v232, v190, v191
	v_cvt_pk_bf16_f32 v233, v192, v193
	v_pk_fma_f32 v[190:191], v[134:135], v[122:123], v[118:119]
	v_pk_fma_f32 v[192:193], v[136:137], v[124:125], v[120:121]
	v_pk_fma_f32 v[194:195], v[130:131], v[106:107], v[102:103]
	v_pk_fma_f32 v[196:197], v[132:133], v[108:109], v[104:105]
	v_pk_fma_f32 v[190:191], v[142:143], v[126:127], v[190:191]
	v_pk_fma_f32 v[192:193], v[144:145], v[128:129], v[192:193]
	v_pk_fma_f32 v[194:195], v[138:139], v[110:111], v[194:195]
	v_pk_fma_f32 v[196:197], v[140:141], v[112:113], v[196:197]
	v_fmac_f32_dpp v190, v158, v114 row_ror:15 row_mask:0xf bank_mask:0xf
	v_fmac_f32_dpp v191, v159, v115 row_ror:15 row_mask:0xf bank_mask:0xf
	v_fmac_f32_dpp v192, v160, v116 row_ror:15 row_mask:0xf bank_mask:0xf
	v_fmac_f32_dpp v193, v161, v117 row_ror:15 row_mask:0xf bank_mask:0xf
	v_fmac_f32_dpp v194, v154, v98 row_ror:15 row_mask:0xf bank_mask:0xf
	v_fmac_f32_dpp v195, v155, v99 row_ror:15 row_mask:0xf bank_mask:0xf
	v_fmac_f32_dpp v196, v156, v100 row_ror:15 row_mask:0xf bank_mask:0xf
	v_fmac_f32_dpp v197, v157, v101 row_ror:15 row_mask:0xf bank_mask:0xf
	v_pk_mul_f32 v[198:199], v[190:191], s[50:51]
	v_pk_mul_f32 v[200:201], v[192:193], s[50:51]
	v_exp_f32_e32 v198, v198
	v_exp_f32_e32 v199, v199
	v_exp_f32_e32 v200, v200
	v_exp_f32_e32 v201, v201
	v_add_f32_e32 v198, 1.0, v198
	v_add_f32_e32 v199, 1.0, v199
	v_add_f32_e32 v200, 1.0, v200
	v_add_f32_e32 v201, 1.0, v201
	v_rcp_f32_e32 v198, v198
	v_rcp_f32_e32 v199, v199
	v_rcp_f32_e32 v200, v200
	v_rcp_f32_e32 v201, v201
	v_pk_mul_f32 v[190:191], v[190:191], v[198:199]
	v_pk_mul_f32 v[192:193], v[192:193], v[200:201]
	v_pk_mul_f32 v[190:191], v[190:191], v[194:195]
	v_pk_mul_f32 v[192:193], v[192:193], v[196:197]
	v_cvt_pk_bf16_f32 v234, v190, v191
	v_cvt_pk_bf16_f32 v235, v192, v193
	v_cmp_gt_i32_e32 vcc, s3, v230
	s_and_b64 vcc, vcc, s[54:55]
	s_nop 0
	v_permlane16_swap_b32_e32 v232, v234
	v_permlane16_swap_b32_e32 v233, v235
	s_and_saveexec_b64 s[0:1], vcc
	global_store_dwordx4 v231, v[232:235], s[12:13]
	s_mov_b64 exec, s[0:1]
	ds_read_b128 v[130:133], v188 offset:64
	ds_read_b128 v[134:137], v188 offset:192
	ds_read_b128 v[138:141], v188 offset:320
	ds_read_b128 v[142:145], v188 offset:448
	ds_read_b128 v[146:149], v188 offset:576
	ds_read_b128 v[150:153], v188 offset:704
	ds_read_b128 v[154:157], v188 offset:832
	ds_read_b128 v[158:161], v188 offset:960
	v_pk_fma_f32 v[190:191], v[94:95], v[122:123], v[118:119]
	v_pk_fma_f32 v[192:193], v[96:97], v[124:125], v[120:121]
	v_pk_fma_f32 v[194:195], v[90:91], v[106:107], v[102:103]
	v_pk_fma_f32 v[196:197], v[92:93], v[108:109], v[104:105]
	v_add_u32_e32 v230, 0x7c, v186
	v_add_u32_e32 v231, 0xaa800, v187
	v_fmac_f32_dpp v190, v70, v126 row_ror:1 row_mask:0xf bank_mask:0xf
	v_fmac_f32_dpp v191, v71, v127 row_ror:1 row_mask:0xf bank_mask:0xf
	v_fmac_f32_dpp v192, v72, v128 row_ror:1 row_mask:0xf bank_mask:0xf
	v_fmac_f32_dpp v193, v73, v129 row_ror:1 row_mask:0xf bank_mask:0xf
	v_fmac_f32_dpp v194, v66, v110 row_ror:1 row_mask:0xf bank_mask:0xf
	v_fmac_f32_dpp v195, v67, v111 row_ror:1 row_mask:0xf bank_mask:0xf
	v_fmac_f32_dpp v196, v68, v112 row_ror:1 row_mask:0xf bank_mask:0xf
	v_fmac_f32_dpp v197, v69, v113 row_ror:1 row_mask:0xf bank_mask:0xf
	v_pk_fma_f32 v[190:191], v[86:87], v[114:115], v[190:191]
	v_pk_fma_f32 v[192:193], v[88:89], v[116:117], v[192:193]
	v_pk_fma_f32 v[194:195], v[82:83], v[98:99], v[194:195]
	v_pk_fma_f32 v[196:197], v[84:85], v[100:101], v[196:197]
	v_pk_mul_f32 v[198:199], v[190:191], s[50:51]
	v_pk_mul_f32 v[200:201], v[192:193], s[50:51]
	v_exp_f32_e32 v198, v198
	v_exp_f32_e32 v199, v199
	v_exp_f32_e32 v200, v200
	v_exp_f32_e32 v201, v201
	v_add_f32_e32 v198, 1.0, v198
	v_add_f32_e32 v199, 1.0, v199
	v_add_f32_e32 v200, 1.0, v200
	v_add_f32_e32 v201, 1.0, v201
	v_rcp_f32_e32 v198, v198
	v_rcp_f32_e32 v199, v199
	v_rcp_f32_e32 v200, v200
	v_rcp_f32_e32 v201, v201
	v_pk_mul_f32 v[190:191], v[190:191], v[198:199]
	v_pk_mul_f32 v[192:193], v[192:193], v[200:201]
	v_pk_mul_f32 v[190:191], v[190:191], v[194:195]
	v_pk_mul_f32 v[192:193], v[192:193], v[196:197]
	v_cvt_pk_bf16_f32 v232, v190, v191
	v_cvt_pk_bf16_f32 v233, v192, v193
	v_pk_fma_f32 v[190:191], v[86:87], v[122:123], v[118:119]
	v_pk_fma_f32 v[192:193], v[88:89], v[124:125], v[120:121]
	v_pk_fma_f32 v[194:195], v[82:83], v[106:107], v[102:103]
	v_pk_fma_f32 v[196:197], v[84:85], v[108:109], v[104:105]
	v_pk_fma_f32 v[190:191], v[94:95], v[126:127], v[190:191]
	v_pk_fma_f32 v[192:193], v[96:97], v[128:129], v[192:193]
	v_pk_fma_f32 v[194:195], v[90:91], v[110:111], v[194:195]
	v_pk_fma_f32 v[196:197], v[92:93], v[112:113], v[196:197]
	v_pk_fma_f32 v[190:191], v[78:79], v[114:115], v[190:191]
	v_pk_fma_f32 v[192:193], v[80:81], v[116:117], v[192:193]
	v_pk_fma_f32 v[194:195], v[74:75], v[98:99], v[194:195]
	v_pk_fma_f32 v[196:197], v[76:77], v[100:101], v[196:197]
	v_pk_mul_f32 v[198:199], v[190:191], s[50:51]
	v_pk_mul_f32 v[200:201], v[192:193], s[50:51]
	v_exp_f32_e32 v198, v198
	v_exp_f32_e32 v199, v199
	v_exp_f32_e32 v200, v200
	v_exp_f32_e32 v201, v201
	v_add_f32_e32 v198, 1.0, v198
	v_add_f32_e32 v199, 1.0, v199
	v_add_f32_e32 v200, 1.0, v200
	v_add_f32_e32 v201, 1.0, v201
	v_rcp_f32_e32 v198, v198
	v_rcp_f32_e32 v199, v199
	v_rcp_f32_e32 v200, v200
	v_rcp_f32_e32 v201, v201
	v_pk_mul_f32 v[190:191], v[190:191], v[198:199]
	v_pk_mul_f32 v[192:193], v[192:193], v[200:201]
	v_pk_mul_f32 v[190:191], v[190:191], v[194:195]
	v_pk_mul_f32 v[192:193], v[192:193], v[196:197]
	v_cvt_pk_bf16_f32 v234, v190, v191
	v_cvt_pk_bf16_f32 v235, v192, v193
	v_cmp_gt_i32_e32 vcc, s3, v230
	s_and_b64 vcc, vcc, s[52:53]
	s_nop 0
	v_permlane16_swap_b32_e32 v232, v234
	v_permlane16_swap_b32_e32 v233, v235
	s_and_saveexec_b64 s[0:1], vcc
	global_store_dwordx4 v231, v[232:235], s[12:13]
	s_mov_b64 exec, s[0:1]
	v_pk_fma_f32 v[190:191], v[78:79], v[122:123], v[118:119]
	v_pk_fma_f32 v[192:193], v[80:81], v[124:125], v[120:121]
	v_pk_fma_f32 v[194:195], v[74:75], v[106:107], v[102:103]
	v_pk_fma_f32 v[196:197], v[76:77], v[108:109], v[104:105]
	v_add_u32_e32 v230, 0x7e, v186
	v_add_u32_e32 v231, 0xad400, v187
	v_pk_fma_f32 v[190:191], v[86:87], v[126:127], v[190:191]
	v_pk_fma_f32 v[192:193], v[88:89], v[128:129], v[192:193]
	v_pk_fma_f32 v[194:195], v[82:83], v[110:111], v[194:195]
	v_pk_fma_f32 v[196:197], v[84:85], v[112:113], v[196:197]
	v_pk_fma_f32 v[190:191], v[70:71], v[114:115], v[190:191]
	v_pk_fma_f32 v[192:193], v[72:73], v[116:117], v[192:193]
	v_pk_fma_f32 v[194:195], v[66:67], v[98:99], v[194:195]
	v_pk_fma_f32 v[196:197], v[68:69], v[100:101], v[196:197]
	v_pk_mul_f32 v[198:199], v[190:191], s[50:51]
	v_pk_mul_f32 v[200:201], v[192:193], s[50:51]
	v_exp_f32_e32 v198, v198
	v_exp_f32_e32 v199, v199
	v_exp_f32_e32 v200, v200
	v_exp_f32_e32 v201, v201
	v_add_f32_e32 v198, 1.0, v198
	v_add_f32_e32 v199, 1.0, v199
	v_add_f32_e32 v200, 1.0, v200
	v_add_f32_e32 v201, 1.0, v201
	v_rcp_f32_e32 v198, v198
	v_rcp_f32_e32 v199, v199
	v_rcp_f32_e32 v200, v200
	v_rcp_f32_e32 v201, v201
	v_pk_mul_f32 v[190:191], v[190:191], v[198:199]
	v_pk_mul_f32 v[192:193], v[192:193], v[200:201]
	v_pk_mul_f32 v[190:191], v[190:191], v[194:195]
	v_pk_mul_f32 v[192:193], v[192:193], v[196:197]
	v_cvt_pk_bf16_f32 v232, v190, v191
	v_cvt_pk_bf16_f32 v233, v192, v193
	v_pk_fma_f32 v[190:191], v[70:71], v[122:123], v[118:119]
	v_pk_fma_f32 v[192:193], v[72:73], v[124:125], v[120:121]
	v_pk_fma_f32 v[194:195], v[66:67], v[106:107], v[102:103]
	v_pk_fma_f32 v[196:197], v[68:69], v[108:109], v[104:105]
	v_pk_fma_f32 v[190:191], v[78:79], v[126:127], v[190:191]
	v_pk_fma_f32 v[192:193], v[80:81], v[128:129], v[192:193]
	v_pk_fma_f32 v[194:195], v[74:75], v[110:111], v[194:195]
	v_pk_fma_f32 v[196:197], v[76:77], v[112:113], v[196:197]
	v_fmac_f32_dpp v190, v94, v114 row_ror:15 row_mask:0xf bank_mask:0xf
	v_fmac_f32_dpp v191, v95, v115 row_ror:15 row_mask:0xf bank_mask:0xf
	v_fmac_f32_dpp v192, v96, v116 row_ror:15 row_mask:0xf bank_mask:0xf
	v_fmac_f32_dpp v193, v97, v117 row_ror:15 row_mask:0xf bank_mask:0xf
	v_fmac_f32_dpp v194, v90, v98 row_ror:15 row_mask:0xf bank_mask:0xf
	v_fmac_f32_dpp v195, v91, v99 row_ror:15 row_mask:0xf bank_mask:0xf
	v_fmac_f32_dpp v196, v92, v100 row_ror:15 row_mask:0xf bank_mask:0xf
	v_fmac_f32_dpp v197, v93, v101 row_ror:15 row_mask:0xf bank_mask:0xf
	v_pk_mul_f32 v[198:199], v[190:191], s[50:51]
	v_pk_mul_f32 v[200:201], v[192:193], s[50:51]
	v_exp_f32_e32 v198, v198
	v_exp_f32_e32 v199, v199
	v_exp_f32_e32 v200, v200
	v_exp_f32_e32 v201, v201
	v_add_f32_e32 v198, 1.0, v198
	v_add_f32_e32 v199, 1.0, v199
	v_add_f32_e32 v200, 1.0, v200
	v_add_f32_e32 v201, 1.0, v201
	v_rcp_f32_e32 v198, v198
	v_rcp_f32_e32 v199, v199
	v_rcp_f32_e32 v200, v200
	v_rcp_f32_e32 v201, v201
	v_pk_mul_f32 v[190:191], v[190:191], v[198:199]
	v_pk_mul_f32 v[192:193], v[192:193], v[200:201]
	v_pk_mul_f32 v[190:191], v[190:191], v[194:195]
	v_pk_mul_f32 v[192:193], v[192:193], v[196:197]
	v_cvt_pk_bf16_f32 v234, v190, v191
	v_cvt_pk_bf16_f32 v235, v192, v193
	v_cmp_gt_i32_e32 vcc, s3, v230
	s_and_b64 vcc, vcc, s[54:55]
	s_nop 0
	v_permlane16_swap_b32_e32 v232, v234
	v_permlane16_swap_b32_e32 v233, v235
	s_and_saveexec_b64 s[0:1], vcc
	global_store_dwordx4 v231, v[232:235], s[12:13]
	s_mov_b64 exec, s[0:1]
	s_waitcnt lgkmcnt(0)
	v_pk_fma_f32 v[190:191], v[62:63], v[134:135], v[142:143]
	v_pk_fma_f32 v[192:193], v[64:65], v[136:137], v[144:145]
	v_pk_fma_f32 v[194:195], v[58:59], v[150:151], v[158:159]
	v_pk_fma_f32 v[196:197], v[60:61], v[152:153], v[160:161]
	v_add_u32_e32 v230, 0, v186
	v_fmac_f32_dpp v190, v38, v130 row_ror:1 row_mask:0xf bank_mask:0xf
	v_fmac_f32_dpp v191, v39, v131 row_ror:1 row_mask:0xf bank_mask:0xf
	v_fmac_f32_dpp v192, v40, v132 row_ror:1 row_mask:0xf bank_mask:0xf
	v_fmac_f32_dpp v193, v41, v133 row_ror:1 row_mask:0xf bank_mask:0xf
	v_fmac_f32_dpp v194, v34, v146 row_ror:1 row_mask:0xf bank_mask:0xf
	v_fmac_f32_dpp v195, v35, v147 row_ror:1 row_mask:0xf bank_mask:0xf
	v_fmac_f32_dpp v196, v36, v148 row_ror:1 row_mask:0xf bank_mask:0xf
	v_fmac_f32_dpp v197, v37, v149 row_ror:1 row_mask:0xf bank_mask:0xf
	v_pk_fma_f32 v[190:191], v[54:55], v[138:139], v[190:191]
	v_pk_fma_f32 v[192:193], v[56:57], v[140:141], v[192:193]
	v_pk_fma_f32 v[194:195], v[50:51], v[154:155], v[194:195]
	v_pk_fma_f32 v[196:197], v[52:53], v[156:157], v[196:197]
	v_pk_mul_f32 v[198:199], v[190:191], s[50:51]
	v_pk_mul_f32 v[200:201], v[192:193], s[50:51]
	v_exp_f32_e32 v198, v198
	v_exp_f32_e32 v199, v199
	v_exp_f32_e32 v200, v200
	v_exp_f32_e32 v201, v201
	v_add_f32_e32 v198, 1.0, v198
	v_add_f32_e32 v199, 1.0, v199
	v_add_f32_e32 v200, 1.0, v200
	v_add_f32_e32 v201, 1.0, v201
	v_rcp_f32_e32 v198, v198
	v_rcp_f32_e32 v199, v199
	v_rcp_f32_e32 v200, v200
	v_rcp_f32_e32 v201, v201
	v_pk_mul_f32 v[190:191], v[190:191], v[198:199]
	v_pk_mul_f32 v[192:193], v[192:193], v[200:201]
	v_pk_mul_f32 v[190:191], v[190:191], v[194:195]
	v_pk_mul_f32 v[192:193], v[192:193], v[196:197]
	v_cvt_pk_bf16_f32 v232, v190, v191
	v_cvt_pk_bf16_f32 v233, v192, v193
	v_pk_fma_f32 v[190:191], v[54:55], v[134:135], v[142:143]
	v_pk_fma_f32 v[192:193], v[56:57], v[136:137], v[144:145]
	v_pk_fma_f32 v[194:195], v[50:51], v[150:151], v[158:159]
	v_pk_fma_f32 v[196:197], v[52:53], v[152:153], v[160:161]
	v_pk_fma_f32 v[190:191], v[62:63], v[130:131], v[190:191]
	v_pk_fma_f32 v[192:193], v[64:65], v[132:133], v[192:193]
	v_pk_fma_f32 v[194:195], v[58:59], v[146:147], v[194:195]
	v_pk_fma_f32 v[196:197], v[60:61], v[148:149], v[196:197]
	v_pk_fma_f32 v[190:191], v[46:47], v[138:139], v[190:191]
	v_pk_fma_f32 v[192:193], v[48:49], v[140:141], v[192:193]
	v_pk_fma_f32 v[194:195], v[42:43], v[154:155], v[194:195]
	v_pk_fma_f32 v[196:197], v[44:45], v[156:157], v[196:197]
	v_pk_mul_f32 v[198:199], v[190:191], s[50:51]
	v_pk_mul_f32 v[200:201], v[192:193], s[50:51]
	v_exp_f32_e32 v198, v198
	v_exp_f32_e32 v199, v199
	v_exp_f32_e32 v200, v200
	v_exp_f32_e32 v201, v201
	v_add_f32_e32 v198, 1.0, v198
	v_add_f32_e32 v199, 1.0, v199
	v_add_f32_e32 v200, 1.0, v200
	v_add_f32_e32 v201, 1.0, v201
	v_rcp_f32_e32 v198, v198
	v_rcp_f32_e32 v199, v199
	v_rcp_f32_e32 v200, v200
	v_rcp_f32_e32 v201, v201
	v_pk_mul_f32 v[190:191], v[190:191], v[198:199]
	v_pk_mul_f32 v[192:193], v[192:193], v[200:201]
	v_pk_mul_f32 v[190:191], v[190:191], v[194:195]
	v_pk_mul_f32 v[192:193], v[192:193], v[196:197]
	v_cvt_pk_bf16_f32 v234, v190, v191
	v_cvt_pk_bf16_f32 v235, v192, v193
	v_cmp_gt_i32_e32 vcc, s3, v230
	s_and_b64 vcc, vcc, s[52:53]
	s_nop 0
	v_permlane16_swap_b32_e32 v232, v234
	v_permlane16_swap_b32_e32 v233, v235
	s_and_saveexec_b64 s[0:1], vcc
	global_store_dwordx4 v187, v[232:235], s[12:13] offset:128
	s_mov_b64 exec, s[0:1]
	v_pk_fma_f32 v[190:191], v[46:47], v[134:135], v[142:143]
	v_pk_fma_f32 v[192:193], v[48:49], v[136:137], v[144:145]
	v_pk_fma_f32 v[194:195], v[42:43], v[150:151], v[158:159]
	v_pk_fma_f32 v[196:197], v[44:45], v[152:153], v[160:161]
	v_add_u32_e32 v230, 2, v186
	v_add_u32_e32 v231, 0x2c00, v187
	v_pk_fma_f32 v[190:191], v[54:55], v[130:131], v[190:191]
	v_pk_fma_f32 v[192:193], v[56:57], v[132:133], v[192:193]
	v_pk_fma_f32 v[194:195], v[50:51], v[146:147], v[194:195]
	v_pk_fma_f32 v[196:197], v[52:53], v[148:149], v[196:197]
	v_pk_fma_f32 v[190:191], v[38:39], v[138:139], v[190:191]
	v_pk_fma_f32 v[192:193], v[40:41], v[140:141], v[192:193]
	v_pk_fma_f32 v[194:195], v[34:35], v[154:155], v[194:195]
	v_pk_fma_f32 v[196:197], v[36:37], v[156:157], v[196:197]
	v_pk_mul_f32 v[198:199], v[190:191], s[50:51]
	v_pk_mul_f32 v[200:201], v[192:193], s[50:51]
	v_exp_f32_e32 v198, v198
	v_exp_f32_e32 v199, v199
	v_exp_f32_e32 v200, v200
	v_exp_f32_e32 v201, v201
	v_add_f32_e32 v198, 1.0, v198
	v_add_f32_e32 v199, 1.0, v199
	v_add_f32_e32 v200, 1.0, v200
	v_add_f32_e32 v201, 1.0, v201
	v_rcp_f32_e32 v198, v198
	v_rcp_f32_e32 v199, v199
	v_rcp_f32_e32 v200, v200
	v_rcp_f32_e32 v201, v201
	v_pk_mul_f32 v[190:191], v[190:191], v[198:199]
	v_pk_mul_f32 v[192:193], v[192:193], v[200:201]
	v_pk_mul_f32 v[190:191], v[190:191], v[194:195]
	v_pk_mul_f32 v[192:193], v[192:193], v[196:197]
	v_cvt_pk_bf16_f32 v232, v190, v191
	v_cvt_pk_bf16_f32 v233, v192, v193
	v_pk_fma_f32 v[190:191], v[38:39], v[134:135], v[142:143]
	v_pk_fma_f32 v[192:193], v[40:41], v[136:137], v[144:145]
	v_pk_fma_f32 v[194:195], v[34:35], v[150:151], v[158:159]
	v_pk_fma_f32 v[196:197], v[36:37], v[152:153], v[160:161]
	v_pk_fma_f32 v[190:191], v[46:47], v[130:131], v[190:191]
	v_pk_fma_f32 v[192:193], v[48:49], v[132:133], v[192:193]
	v_pk_fma_f32 v[194:195], v[42:43], v[146:147], v[194:195]
	v_pk_fma_f32 v[196:197], v[44:45], v[148:149], v[196:197]
	v_fmac_f32_dpp v190, v62, v138 row_ror:15 row_mask:0xf bank_mask:0xf
	v_fmac_f32_dpp v191, v63, v139 row_ror:15 row_mask:0xf bank_mask:0xf
	v_fmac_f32_dpp v192, v64, v140 row_ror:15 row_mask:0xf bank_mask:0xf
	v_fmac_f32_dpp v193, v65, v141 row_ror:15 row_mask:0xf bank_mask:0xf
	v_fmac_f32_dpp v194, v58, v154 row_ror:15 row_mask:0xf bank_mask:0xf
	v_fmac_f32_dpp v195, v59, v155 row_ror:15 row_mask:0xf bank_mask:0xf
	v_fmac_f32_dpp v196, v60, v156 row_ror:15 row_mask:0xf bank_mask:0xf
	v_fmac_f32_dpp v197, v61, v157 row_ror:15 row_mask:0xf bank_mask:0xf
	v_pk_mul_f32 v[198:199], v[190:191], s[50:51]
	v_pk_mul_f32 v[200:201], v[192:193], s[50:51]
	v_exp_f32_e32 v198, v198
	v_exp_f32_e32 v199, v199
	v_exp_f32_e32 v200, v200
	v_exp_f32_e32 v201, v201
	v_add_f32_e32 v198, 1.0, v198
	v_add_f32_e32 v199, 1.0, v199
	v_add_f32_e32 v200, 1.0, v200
	v_add_f32_e32 v201, 1.0, v201
	v_rcp_f32_e32 v198, v198
	v_rcp_f32_e32 v199, v199
	v_rcp_f32_e32 v200, v200
	v_rcp_f32_e32 v201, v201
	v_pk_mul_f32 v[190:191], v[190:191], v[198:199]
	v_pk_mul_f32 v[192:193], v[192:193], v[200:201]
	v_pk_mul_f32 v[190:191], v[190:191], v[194:195]
	v_pk_mul_f32 v[192:193], v[192:193], v[196:197]
	v_cvt_pk_bf16_f32 v234, v190, v191
	v_cvt_pk_bf16_f32 v235, v192, v193
	v_cmp_gt_i32_e32 vcc, s3, v230
	s_and_b64 vcc, vcc, s[54:55]
	s_nop 0
	v_permlane16_swap_b32_e32 v232, v234
	v_permlane16_swap_b32_e32 v233, v235
	s_and_saveexec_b64 s[0:1], vcc
	global_store_dwordx4 v231, v[232:235], s[12:13] offset:128
	s_mov_b64 exec, s[0:1]
	v_pk_fma_f32 v[190:191], v[30:31], v[134:135], v[142:143]
	v_pk_fma_f32 v[192:193], v[32:33], v[136:137], v[144:145]
	v_pk_fma_f32 v[194:195], v[26:27], v[150:151], v[158:159]
	v_pk_fma_f32 v[196:197], v[28:29], v[152:153], v[160:161]
	v_add_u32_e32 v230, 0x7c, v186
	v_add_u32_e32 v231, 0xaa800, v187
	v_fmac_f32_dpp v190, v6, v130 row_ror:1 row_mask:0xf bank_mask:0xf
	v_fmac_f32_dpp v191, v7, v131 row_ror:1 row_mask:0xf bank_mask:0xf
	v_fmac_f32_dpp v192, v8, v132 row_ror:1 row_mask:0xf bank_mask:0xf
	v_fmac_f32_dpp v193, v9, v133 row_ror:1 row_mask:0xf bank_mask:0xf
	v_fmac_f32_dpp v194, v2, v146 row_ror:1 row_mask:0xf bank_mask:0xf
	v_fmac_f32_dpp v195, v3, v147 row_ror:1 row_mask:0xf bank_mask:0xf
	v_fmac_f32_dpp v196, v4, v148 row_ror:1 row_mask:0xf bank_mask:0xf
	v_fmac_f32_dpp v197, v5, v149 row_ror:1 row_mask:0xf bank_mask:0xf
	v_pk_fma_f32 v[190:191], v[22:23], v[138:139], v[190:191]
	v_pk_fma_f32 v[192:193], v[24:25], v[140:141], v[192:193]
	v_pk_fma_f32 v[194:195], v[18:19], v[154:155], v[194:195]
	v_pk_fma_f32 v[196:197], v[20:21], v[156:157], v[196:197]
	v_pk_mul_f32 v[198:199], v[190:191], s[50:51]
	v_pk_mul_f32 v[200:201], v[192:193], s[50:51]
	v_exp_f32_e32 v198, v198
	v_exp_f32_e32 v199, v199
	v_exp_f32_e32 v200, v200
	v_exp_f32_e32 v201, v201
	v_add_f32_e32 v198, 1.0, v198
	v_add_f32_e32 v199, 1.0, v199
	v_add_f32_e32 v200, 1.0, v200
	v_add_f32_e32 v201, 1.0, v201
	v_rcp_f32_e32 v198, v198
	v_rcp_f32_e32 v199, v199
	v_rcp_f32_e32 v200, v200
	v_rcp_f32_e32 v201, v201
	v_pk_mul_f32 v[190:191], v[190:191], v[198:199]
	v_pk_mul_f32 v[192:193], v[192:193], v[200:201]
	v_pk_mul_f32 v[190:191], v[190:191], v[194:195]
	v_pk_mul_f32 v[192:193], v[192:193], v[196:197]
	v_cvt_pk_bf16_f32 v232, v190, v191
	v_cvt_pk_bf16_f32 v233, v192, v193
	v_pk_fma_f32 v[190:191], v[22:23], v[134:135], v[142:143]
	v_pk_fma_f32 v[192:193], v[24:25], v[136:137], v[144:145]
	v_pk_fma_f32 v[194:195], v[18:19], v[150:151], v[158:159]
	v_pk_fma_f32 v[196:197], v[20:21], v[152:153], v[160:161]
	v_pk_fma_f32 v[190:191], v[30:31], v[130:131], v[190:191]
	v_pk_fma_f32 v[192:193], v[32:33], v[132:133], v[192:193]
	v_pk_fma_f32 v[194:195], v[26:27], v[146:147], v[194:195]
	v_pk_fma_f32 v[196:197], v[28:29], v[148:149], v[196:197]
	v_pk_fma_f32 v[190:191], v[14:15], v[138:139], v[190:191]
	v_pk_fma_f32 v[192:193], v[16:17], v[140:141], v[192:193]
	v_pk_fma_f32 v[194:195], v[10:11], v[154:155], v[194:195]
	v_pk_fma_f32 v[196:197], v[12:13], v[156:157], v[196:197]
	v_pk_mul_f32 v[198:199], v[190:191], s[50:51]
	v_pk_mul_f32 v[200:201], v[192:193], s[50:51]
	v_exp_f32_e32 v198, v198
	v_exp_f32_e32 v199, v199
	v_exp_f32_e32 v200, v200
	v_exp_f32_e32 v201, v201
	v_add_f32_e32 v198, 1.0, v198
	v_add_f32_e32 v199, 1.0, v199
	v_add_f32_e32 v200, 1.0, v200
	v_add_f32_e32 v201, 1.0, v201
	v_rcp_f32_e32 v198, v198
	v_rcp_f32_e32 v199, v199
	v_rcp_f32_e32 v200, v200
	v_rcp_f32_e32 v201, v201
	v_pk_mul_f32 v[190:191], v[190:191], v[198:199]
	v_pk_mul_f32 v[192:193], v[192:193], v[200:201]
	v_pk_mul_f32 v[190:191], v[190:191], v[194:195]
	v_pk_mul_f32 v[192:193], v[192:193], v[196:197]
	v_cvt_pk_bf16_f32 v234, v190, v191
	v_cvt_pk_bf16_f32 v235, v192, v193
	v_cmp_gt_i32_e32 vcc, s3, v230
	s_and_b64 vcc, vcc, s[52:53]
	s_nop 0
	v_permlane16_swap_b32_e32 v232, v234
	v_permlane16_swap_b32_e32 v233, v235
	s_and_saveexec_b64 s[0:1], vcc
	global_store_dwordx4 v231, v[232:235], s[12:13] offset:128
	s_mov_b64 exec, s[0:1]
	v_pk_fma_f32 v[190:191], v[14:15], v[134:135], v[142:143]
	v_pk_fma_f32 v[192:193], v[16:17], v[136:137], v[144:145]
	v_pk_fma_f32 v[194:195], v[10:11], v[150:151], v[158:159]
	v_pk_fma_f32 v[196:197], v[12:13], v[152:153], v[160:161]
	v_add_u32_e32 v230, 0x7e, v186
	v_add_u32_e32 v231, 0xad400, v187
	v_pk_fma_f32 v[190:191], v[22:23], v[130:131], v[190:191]
	v_pk_fma_f32 v[192:193], v[24:25], v[132:133], v[192:193]
	v_pk_fma_f32 v[194:195], v[18:19], v[146:147], v[194:195]
	v_pk_fma_f32 v[196:197], v[20:21], v[148:149], v[196:197]
	v_pk_fma_f32 v[190:191], v[6:7], v[138:139], v[190:191]
	v_pk_fma_f32 v[192:193], v[8:9], v[140:141], v[192:193]
	v_pk_fma_f32 v[194:195], v[2:3], v[154:155], v[194:195]
	v_pk_fma_f32 v[196:197], v[4:5], v[156:157], v[196:197]
	v_pk_mul_f32 v[198:199], v[190:191], s[50:51]
	v_pk_mul_f32 v[200:201], v[192:193], s[50:51]
	v_exp_f32_e32 v198, v198
	v_exp_f32_e32 v199, v199
	v_exp_f32_e32 v200, v200
	v_exp_f32_e32 v201, v201
	v_add_f32_e32 v198, 1.0, v198
	v_add_f32_e32 v199, 1.0, v199
	v_add_f32_e32 v200, 1.0, v200
	v_add_f32_e32 v201, 1.0, v201
	v_rcp_f32_e32 v198, v198
	v_rcp_f32_e32 v199, v199
	v_rcp_f32_e32 v200, v200
	v_rcp_f32_e32 v201, v201
	v_pk_mul_f32 v[190:191], v[190:191], v[198:199]
	v_pk_mul_f32 v[192:193], v[192:193], v[200:201]
	v_pk_mul_f32 v[190:191], v[190:191], v[194:195]
	v_pk_mul_f32 v[192:193], v[192:193], v[196:197]
	v_cvt_pk_bf16_f32 v232, v190, v191
	v_cvt_pk_bf16_f32 v233, v192, v193
	v_pk_fma_f32 v[190:191], v[6:7], v[134:135], v[142:143]
	v_pk_fma_f32 v[192:193], v[8:9], v[136:137], v[144:145]
	v_pk_fma_f32 v[194:195], v[2:3], v[150:151], v[158:159]
	v_pk_fma_f32 v[196:197], v[4:5], v[152:153], v[160:161]
	v_pk_fma_f32 v[190:191], v[14:15], v[130:131], v[190:191]
	v_pk_fma_f32 v[192:193], v[16:17], v[132:133], v[192:193]
	v_pk_fma_f32 v[194:195], v[10:11], v[146:147], v[194:195]
	v_pk_fma_f32 v[196:197], v[12:13], v[148:149], v[196:197]
	v_fmac_f32_dpp v190, v30, v138 row_ror:15 row_mask:0xf bank_mask:0xf
	v_fmac_f32_dpp v191, v31, v139 row_ror:15 row_mask:0xf bank_mask:0xf
	v_fmac_f32_dpp v192, v32, v140 row_ror:15 row_mask:0xf bank_mask:0xf
	v_fmac_f32_dpp v193, v33, v141 row_ror:15 row_mask:0xf bank_mask:0xf
	v_fmac_f32_dpp v194, v26, v154 row_ror:15 row_mask:0xf bank_mask:0xf
	v_fmac_f32_dpp v195, v27, v155 row_ror:15 row_mask:0xf bank_mask:0xf
	v_fmac_f32_dpp v196, v28, v156 row_ror:15 row_mask:0xf bank_mask:0xf
	v_fmac_f32_dpp v197, v29, v157 row_ror:15 row_mask:0xf bank_mask:0xf
	v_pk_mul_f32 v[198:199], v[190:191], s[50:51]
	v_pk_mul_f32 v[200:201], v[192:193], s[50:51]
	v_exp_f32_e32 v198, v198
	v_exp_f32_e32 v199, v199
	v_exp_f32_e32 v200, v200
	v_exp_f32_e32 v201, v201
	v_add_f32_e32 v198, 1.0, v198
	v_add_f32_e32 v199, 1.0, v199
	v_add_f32_e32 v200, 1.0, v200
	v_add_f32_e32 v201, 1.0, v201
	v_rcp_f32_e32 v198, v198
	v_rcp_f32_e32 v199, v199
	v_rcp_f32_e32 v200, v200
	v_rcp_f32_e32 v201, v201
	v_pk_mul_f32 v[190:191], v[190:191], v[198:199]
	v_pk_mul_f32 v[192:193], v[192:193], v[200:201]
	v_pk_mul_f32 v[190:191], v[190:191], v[194:195]
	v_pk_mul_f32 v[192:193], v[192:193], v[196:197]
	v_cvt_pk_bf16_f32 v234, v190, v191
	v_cvt_pk_bf16_f32 v235, v192, v193
	v_cmp_gt_i32_e32 vcc, s3, v230
	s_and_b64 vcc, vcc, s[54:55]
	s_nop 0
	v_permlane16_swap_b32_e32 v232, v234
	v_permlane16_swap_b32_e32 v233, v235
	s_and_saveexec_b64 s[0:1], vcc
	global_store_dwordx4 v231, v[232:235], s[12:13] offset:128
	s_mov_b64 exec, s[0:1]
